# v36 + wave reductions of the row-wise passes: 6 ds_bpermute round trips replaced by 4 DPP row ops + 4 v_readlane (same summation order)
# speedup vs baseline: 1.0051x; 1.0051x over previous
; __device__ __forceinline__ float bflo(unsigned w) { return __uint_as_float(w << 16); }
; __device__ __forceinline__ float bfhi(unsigned w) { return __uint_as_float(w & 0xffff0000u); }
; __device__ __forceinline__ unsigned pkbf(float lo, float hi) { return pg8::cvt_pk_bf16(lo, hi); }
; __device__ __forceinline__ void norm_row(const float* src, const bf16_t* add, const float* gain, bf16_t* ob, float* of, int lane) {
;     f32x4 v[4]; float s = 0.f;
; #pragma unroll
;     for (int j = 0; j < 4; ++j) { v[j] = *((const f32x4*)src + lane + 64 * j);
;         if (add) { const u32x2 d = *((const u32x2*)add + lane + 64 * j); v[j][0] += bflo(d.x); v[j][1] += bfhi(d.x); v[j][2] += bflo(d.y); v[j][3] += bfhi(d.y); }
;         s += (v[j][0] * v[j][0] + v[j][1] * v[j][1]) + (v[j][2] * v[j][2] + v[j][3] * v[j][3]); }
;     const float rstd = 1.0f / sqrtf(wave_sum(s) * (1.f / DM) + NORM_EPS);
; #pragma unroll
;     for (int j = 0; j < 4; ++j) { const f32x4 g = *((const f32x4*)gain + lane + 64 * j); const f32x4 o = v[j] * rstd * g;
;         if (ob) { u32x2 w; w.x = pkbf(o[0], o[1]); w.y = pkbf(o[2], o[3]); *((u32x2*)ob + lane + 64 * j) = w; }
;         else *((f32x4*)of + lane + 64 * j) = o; }
; }
.LBB0_71:
	s_add_i32 s0, s6, 0xffff8000
	s_cmp_lt_i32 s6, 0x8000
	s_cselect_b32 s1, s7, 0
	s_cselect_b32 s0, s6, s0
	s_cselect_b32 s8, s17, s19
	s_cselect_b32 s9, s16, s18
	s_lshl_b64 s[0:1], s[0:1], 12
	s_add_u32 s0, s9, s0
	s_addc_u32 s1, s8, s1
	global_load_dwordx4 v[14:17], v11, s[0:1] nt
	global_load_dwordx4 v[18:21], v11, s[0:1] offset:1024 nt
	global_load_dwordx4 v[22:25], v11, s[0:1] offset:2048 nt
	global_load_dwordx4 v[26:29], v11, s[0:1] offset:3072 nt
	global_load_dwordx4 v[30:33], v[2:3], off
	s_add_u32 s6, s6, s88
	s_addc_u32 s7, s7, s89
	s_cmp_gt_i32 s6, 0xbfff
	s_waitcnt vmcnt(4)
	v_pk_mul_f32 v[34:35], v[16:17], v[16:17]
	v_pk_mul_f32 v[36:37], v[14:15], v[14:15]
	s_waitcnt vmcnt(3)
	v_pk_mul_f32 v[38:39], v[20:21], v[20:21]
	v_pk_mul_f32 v[40:41], v[18:19], v[18:19]
	v_pk_mov_b32 v[46:47], v[36:37], v[34:35] op_sel:[1,0]
	v_mov_b32_e32 v37, v35
	v_pk_mov_b32 v[34:35], v[40:41], v[38:39] op_sel:[1,0]
	v_mov_b32_e32 v41, v39
	s_waitcnt vmcnt(1)
	v_mul_f32_e32 v45, v26, v26
	v_mul_f32_e32 v42, v23, v23
	v_mul_f32_e32 v44, v25, v25
	v_pk_add_f32 v[36:37], v[46:47], v[36:37]
	v_pk_add_f32 v[34:35], v[34:35], v[40:41]
	v_mul_f32_e32 v48, v27, v27
	v_mul_f32_e32 v49, v28, v28
	v_mul_f32_e32 v50, v29, v29
	v_pk_fma_f32 v[38:39], v[22:23], v[22:23], v[42:43] op_sel_hi:[1,1,0]
	v_pk_fma_f32 v[42:43], v[24:25], v[24:25], v[44:45] op_sel_hi:[1,1,0]
	v_pk_add_f32 v[36:37], v[36:37], v[36:37] op_sel:[0,1] op_sel_hi:[1,0]
	v_pk_add_f32 v[34:35], v[34:35], v[34:35] op_sel:[0,1] op_sel_hi:[1,0]
	v_mov_b32_e32 v39, v49
	v_mov_b32_e32 v43, v50
	v_mov_b32_e32 v37, v45
	v_mov_b32_e32 v35, v48
	v_pk_add_f32 v[38:39], v[38:39], v[42:43]
	v_pk_add_f32 v[34:35], v[36:37], v[34:35]
	s_nop 0
	v_pk_add_f32 v[34:35], v[34:35], v[38:39]
	s_nop 0
	v_add_f32_e32 v34, v34, v35
	s_nop 1
	v_add_f32_dpp v34, v34, v34 quad_perm:[1,0,3,2] row_mask:0xf bank_mask:0xf bound_ctrl:1
	s_nop 1
	v_add_f32_dpp v34, v34, v34 quad_perm:[2,3,0,1] row_mask:0xf bank_mask:0xf bound_ctrl:1
	s_nop 1
	v_add_f32_dpp v34, v34, v34 row_half_mirror row_mask:0xf bank_mask:0xf bound_ctrl:1
	s_nop 1
	v_add_f32_dpp v34, v34, v34 row_mirror row_mask:0xf bank_mask:0xf bound_ctrl:1
	s_nop 0
	v_readlane_b32 s98, v34, 0
	v_readlane_b32 s99, v34, 16
	v_readlane_b32 s100, v34, 32
	v_readlane_b32 s101, v34, 48
	v_mov_b32_e32 v34, s98
	v_add_f32_e32 v34, s99, v34
	v_mov_b32_e32 v35, s100
	v_add_f32_e32 v35, s101, v35
	v_add_f32_e32 v34, v34, v35
	v_fmamk_f32 v34, v34, 0x3a800000, v12
	v_mul_f32_e32 v35, 0x4f800000, v34
	v_cmp_gt_f32_e32 vcc, s3, v34
	s_nop 1
	v_cndmask_b32_e32 v34, v34, v35, vcc
	v_sqrt_f32_e32 v35, v34
	s_nop 0
	v_add_u32_e32 v36, -1, v35
	v_add_u32_e32 v37, 1, v35
	v_fma_f32 v38, -v36, v35, v34
	v_fma_f32 v39, -v37, v35, v34
	v_cmp_ge_f32_e64 s[0:1], 0, v38
	s_nop 1
	v_cndmask_b32_e64 v35, v35, v36, s[0:1]
	v_cmp_lt_f32_e64 s[0:1], 0, v39
	s_nop 1
	v_cndmask_b32_e64 v35, v35, v37, s[0:1]
	v_mul_f32_e32 v36, 0x37800000, v35
	v_cndmask_b32_e32 v35, v35, v36, vcc
	v_cmp_class_f32_e32 vcc, v34, v13
	s_nop 1
	v_cndmask_b32_e32 v34, v35, v34, vcc
	v_div_scale_f32 v35, s[0:1], v34, v34, 1.0
	v_rcp_f32_e32 v37, v35
	v_div_scale_f32 v36, vcc, 1.0, v34, 1.0
	v_fma_f32 v38, -v35, v37, 1.0
	v_fmac_f32_e32 v37, v38, v37
	v_mul_f32_e32 v38, v36, v37
	v_fma_f32 v39, -v35, v38, v36
	v_fmac_f32_e32 v38, v39, v37
	v_fma_f32 v35, -v35, v38, v36
	v_div_fmas_f32 v35, v35, v37, v38
	v_div_fixup_f32 v34, v35, v34, 1.0
	v_pk_mul_f32 v[14:15], v[14:15], v[34:35] op_sel_hi:[1,0]
	v_pk_mul_f32 v[16:17], v[16:17], v[34:35] op_sel_hi:[1,0]
	s_waitcnt vmcnt(0)
	v_pk_mul_f32 v[14:15], v[30:31], v[14:15]
	v_pk_mul_f32 v[16:17], v[32:33], v[16:17]
	v_cvt_pk_bf16_f32 v14, v14, v15
	v_pk_mul_f32 v[18:19], v[18:19], v[34:35] op_sel_hi:[1,0]
	v_cvt_pk_bf16_f32 v15, v16, v17
	global_store_dwordx2 v[4:5], v[14:15], off
	global_load_dwordx4 v[14:17], v[2:3], off offset:1024
	v_pk_mul_f32 v[20:21], v[20:21], v[34:35] op_sel_hi:[1,0]
	s_waitcnt vmcnt(0)
	v_pk_mul_f32 v[14:15], v[14:15], v[18:19]
	v_pk_mul_f32 v[16:17], v[16:17], v[20:21]
	v_cvt_pk_bf16_f32 v14, v14, v15
	v_pk_mul_f32 v[18:19], v[22:23], v[34:35] op_sel_hi:[1,0]
	v_cvt_pk_bf16_f32 v15, v16, v17
	global_store_dwordx2 v[4:5], v[14:15], off offset:512
	global_load_dwordx4 v[14:17], v[2:3], off offset:2048
	v_pk_mul_f32 v[20:21], v[24:25], v[34:35] op_sel_hi:[1,0]
	s_waitcnt vmcnt(0)
	v_pk_mul_f32 v[14:15], v[14:15], v[18:19]
	v_pk_mul_f32 v[16:17], v[16:17], v[20:21]
	v_cvt_pk_bf16_f32 v14, v14, v15
	v_pk_mul_f32 v[18:19], v[26:27], v[34:35] op_sel_hi:[1,0]
	v_cvt_pk_bf16_f32 v15, v16, v17
	global_store_dwordx2 v[4:5], v[14:15], off offset:1024
	global_load_dwordx4 v[14:17], v[2:3], off offset:3072
	v_pk_mul_f32 v[20:21], v[28:29], v[34:35] op_sel_hi:[1,0]
	s_waitcnt vmcnt(0)
	v_pk_mul_f32 v[14:15], v[18:19], v[14:15]
	v_pk_mul_f32 v[16:17], v[20:21], v[16:17]
	v_cvt_pk_bf16_f32 v14, v14, v15
	s_nop 0
	v_cvt_pk_bf16_f32 v15, v16, v17
	global_store_dwordx2 v[4:5], v[14:15], off offset:1536
	v_lshl_add_u64 v[4:5], v[4:5], 0, s[4:5]
	s_cbranch_scc0 .LBB0_71

; __device__ __forceinline__ float bflo(unsigned w) { return __uint_as_float(w << 16); }
; __device__ __forceinline__ float bfhi(unsigned w) { return __uint_as_float(w & 0xffff0000u); }
; __device__ __forceinline__ unsigned pkbf(float lo, float hi) { return pg8::cvt_pk_bf16(lo, hi); }
; __device__ __forceinline__ void norm_row(const float* src, const bf16_t* add, const float* gain, bf16_t* ob, float* of, int lane) {
;     f32x4 v[4]; float s = 0.f;
; #pragma unroll
;     for (int j = 0; j < 4; ++j) { v[j] = *((const f32x4*)src + lane + 64 * j);
;         if (add) { const u32x2 d = *((const u32x2*)add + lane + 64 * j); v[j][0] += bflo(d.x); v[j][1] += bfhi(d.x); v[j][2] += bflo(d.y); v[j][3] += bfhi(d.y); }
;         s += (v[j][0] * v[j][0] + v[j][1] * v[j][1]) + (v[j][2] * v[j][2] + v[j][3] * v[j][3]); }
;     const float rstd = 1.0f / sqrtf(wave_sum(s) * (1.f / DM) + NORM_EPS);
; #pragma unroll
;     for (int j = 0; j < 4; ++j) { const f32x4 g = *((const f32x4*)gain + lane + 64 * j); const f32x4 o = v[j] * rstd * g;
;         if (ob) { u32x2 w; w.x = pkbf(o[0], o[1]); w.y = pkbf(o[2], o[3]); *((u32x2*)ob + lane + 64 * j) = w; }
;         else *((f32x4*)of + lane + 64 * j) = o; }
; }
.LBB0_284:
	s_add_i32 s12, s6, 0xffff8000
	v_add_co_u32_e64 v16, s[0:1], s8, v2
	v_add_co_u32_e32 v14, vcc, s3, v2
	s_nop 0
	v_addc_co_u32_e64 v17, s[0:1], -1, v3, s[0:1]
	s_cmp_lt_i32 s6, 0x8000
	v_addc_co_u32_e32 v15, vcc, -1, v3, vcc
	s_cselect_b32 s1, s7, 0
	s_cselect_b32 s0, s6, s12
	global_load_dwordx2 v[34:35], v[14:15], off nt
	global_load_dwordx2 v[36:37], v[16:17], off offset:-3584 nt
	s_cselect_b32 s12, s17, s19
	s_cselect_b32 s13, s16, s18
	s_lshl_b64 s[0:1], s[0:1], 12
	global_load_dwordx2 v[38:39], v[16:17], off offset:-3072 nt
	global_load_dwordx2 v[40:41], v[16:17], off offset:-2560 nt
	s_add_u32 s0, s13, s0
	s_addc_u32 s1, s12, s1
	global_load_dwordx4 v[14:17], v10, s[0:1] nt
	global_load_dwordx4 v[18:21], v10, s[0:1] offset:1024 nt
	global_load_dwordx4 v[22:25], v10, s[0:1] offset:2048 nt
	global_load_dwordx4 v[26:29], v10, s[0:1] offset:3072 nt
	global_load_dwordx4 v[30:33], v[0:1], off
	s_add_u32 s6, s6, s88
	s_addc_u32 s7, s7, s89
	s_cmp_gt_i32 s6, 0xbfff
	s_waitcnt vmcnt(8)
	v_lshlrev_b32_e32 v42, 16, v34
	v_and_b32_e32 v43, 0xffff0000, v34
	v_lshlrev_b32_e32 v34, 16, v35
	v_and_b32_e32 v35, 0xffff0000, v35
	s_waitcnt vmcnt(7)
	v_lshlrev_b32_e32 v44, 16, v36
	v_and_b32_e32 v45, 0xffff0000, v36
	v_lshlrev_b32_e32 v36, 16, v37
	v_and_b32_e32 v37, 0xffff0000, v37
	s_waitcnt vmcnt(5)
	v_lshlrev_b32_e32 v48, 16, v40
	v_and_b32_e32 v49, 0xffff0000, v40
	v_lshlrev_b32_e32 v40, 16, v41
	v_and_b32_e32 v41, 0xffff0000, v41
	s_waitcnt vmcnt(4)
	v_pk_add_f32 v[14:15], v[14:15], v[42:43]
	v_pk_add_f32 v[16:17], v[16:17], v[34:35]
	s_waitcnt vmcnt(3)
	v_pk_add_f32 v[18:19], v[18:19], v[44:45]
	v_pk_add_f32 v[20:21], v[20:21], v[36:37]
	v_lshlrev_b32_e32 v46, 16, v38
	v_and_b32_e32 v47, 0xffff0000, v38
	v_lshlrev_b32_e32 v38, 16, v39
	v_and_b32_e32 v39, 0xffff0000, v39
	s_waitcnt vmcnt(1)
	v_pk_add_f32 v[28:29], v[28:29], v[40:41]
	v_mov_b32_e32 v36, v15
	v_mov_b32_e32 v37, v17
	v_mov_b32_e32 v40, v19
	v_mov_b32_e32 v41, v21
	v_pk_add_f32 v[22:23], v[22:23], v[46:47]
	v_pk_add_f32 v[24:25], v[24:25], v[38:39]
	v_mov_b32_e32 v34, v14
	v_mov_b32_e32 v35, v16
	v_mov_b32_e32 v38, v18
	v_mov_b32_e32 v39, v20
	v_pk_mul_f32 v[36:37], v[36:37], v[36:37]
	v_pk_mul_f32 v[40:41], v[40:41], v[40:41]
	v_pk_add_f32 v[26:27], v[26:27], v[48:49]
	v_mul_f32_e32 v42, v23, v23
	v_mul_f32_e32 v44, v25, v25
	v_pk_fma_f32 v[34:35], v[34:35], v[34:35], v[36:37]
	v_pk_fma_f32 v[36:37], v[38:39], v[38:39], v[40:41]
	v_pk_mul_f32 v[46:47], v[26:27], v[26:27]
	v_pk_mul_f32 v[48:49], v[28:29], v[28:29]
	v_pk_fma_f32 v[42:43], v[22:23], v[22:23], v[42:43] op_sel_hi:[1,1,0]
	v_pk_fma_f32 v[44:45], v[24:25], v[24:25], v[44:45] op_sel_hi:[1,1,0]
	v_pk_add_f32 v[34:35], v[34:35], v[34:35] op_sel:[0,1] op_sel_hi:[1,0]
	v_pk_add_f32 v[36:37], v[36:37], v[36:37] op_sel:[0,1] op_sel_hi:[1,0]
	v_mov_b32_e32 v43, v48
	v_mov_b32_e32 v45, v49
	v_mov_b32_e32 v35, v46
	v_mov_b32_e32 v37, v47
	v_pk_add_f32 v[38:39], v[42:43], v[44:45]
	v_pk_add_f32 v[34:35], v[34:35], v[36:37]
	s_nop 0
	v_pk_add_f32 v[34:35], v[34:35], v[38:39]
	s_nop 0
	v_add_f32_e32 v13, v34, v35
	s_nop 1
	v_add_f32_dpp v13, v13, v13 quad_perm:[1,0,3,2] row_mask:0xf bank_mask:0xf bound_ctrl:1
	s_nop 1
	v_add_f32_dpp v13, v13, v13 quad_perm:[2,3,0,1] row_mask:0xf bank_mask:0xf bound_ctrl:1
	s_nop 1
	v_add_f32_dpp v13, v13, v13 row_half_mirror row_mask:0xf bank_mask:0xf bound_ctrl:1
	s_nop 1
	v_add_f32_dpp v13, v13, v13 row_mirror row_mask:0xf bank_mask:0xf bound_ctrl:1
	s_nop 0
	v_readlane_b32 s98, v13, 0
	v_readlane_b32 s99, v13, 16
	v_readlane_b32 s100, v13, 32
	v_readlane_b32 s101, v13, 48
	v_mov_b32_e32 v13, s98
	v_add_f32_e32 v13, s99, v13
	v_mov_b32_e32 v34, s100
	v_add_f32_e32 v34, s101, v34
	v_add_f32_e32 v13, v13, v34
	v_fmamk_f32 v13, v13, 0x3a800000, v11
	v_mul_f32_e32 v34, 0x4f800000, v13
	v_cmp_gt_f32_e32 vcc, s9, v13
	s_nop 1
	v_cndmask_b32_e32 v13, v13, v34, vcc
	v_sqrt_f32_e32 v34, v13
	s_nop 0
	v_add_u32_e32 v35, -1, v34
	v_add_u32_e32 v36, 1, v34
	v_fma_f32 v37, -v35, v34, v13
	v_fma_f32 v38, -v36, v34, v13
	v_cmp_ge_f32_e64 s[0:1], 0, v37
	s_nop 1
	v_cndmask_b32_e64 v34, v34, v35, s[0:1]
	v_cmp_lt_f32_e64 s[0:1], 0, v38
	s_nop 1
	v_cndmask_b32_e64 v34, v34, v36, s[0:1]
	v_mul_f32_e32 v35, 0x37800000, v34
	v_cndmask_b32_e32 v34, v34, v35, vcc
	v_cmp_class_f32_e32 vcc, v13, v12
	s_nop 1
	v_cndmask_b32_e32 v13, v34, v13, vcc
	v_div_scale_f32 v34, s[0:1], v13, v13, 1.0
	v_rcp_f32_e32 v36, v34
	v_div_scale_f32 v35, vcc, 1.0, v13, 1.0
	v_fma_f32 v37, -v34, v36, 1.0
	v_fmac_f32_e32 v36, v37, v36
	v_mul_f32_e32 v37, v35, v36
	v_fma_f32 v38, -v34, v37, v35
	v_fmac_f32_e32 v37, v38, v36
	v_fma_f32 v34, -v34, v37, v35
	v_div_fmas_f32 v34, v34, v36, v37
	v_div_fixup_f32 v34, v34, v13, 1.0
	v_pk_mul_f32 v[14:15], v[14:15], v[34:35] op_sel_hi:[1,0]
	v_pk_mul_f32 v[16:17], v[16:17], v[34:35] op_sel_hi:[1,0]
	s_waitcnt vmcnt(0)
	v_pk_mul_f32 v[14:15], v[30:31], v[14:15]
	v_pk_mul_f32 v[16:17], v[32:33], v[16:17]
	v_cvt_pk_bf16_f32 v14, v14, v15
	v_pk_mul_f32 v[18:19], v[18:19], v[34:35] op_sel_hi:[1,0]
	v_cvt_pk_bf16_f32 v15, v16, v17
	global_store_dwordx2 v[2:3], v[14:15], off
	global_load_dwordx4 v[14:17], v[0:1], off offset:1024
	v_pk_mul_f32 v[20:21], v[20:21], v[34:35] op_sel_hi:[1,0]
	s_waitcnt vmcnt(0)
	v_pk_mul_f32 v[14:15], v[14:15], v[18:19]
	v_pk_mul_f32 v[16:17], v[16:17], v[20:21]
	v_cvt_pk_bf16_f32 v14, v14, v15
	v_pk_mul_f32 v[18:19], v[22:23], v[34:35] op_sel_hi:[1,0]
	v_cvt_pk_bf16_f32 v15, v16, v17
	global_store_dwordx2 v[2:3], v[14:15], off offset:512
	global_load_dwordx4 v[14:17], v[0:1], off offset:2048
	v_pk_mul_f32 v[20:21], v[24:25], v[34:35] op_sel_hi:[1,0]
	s_waitcnt vmcnt(0)
	v_pk_mul_f32 v[14:15], v[14:15], v[18:19]
	v_pk_mul_f32 v[16:17], v[16:17], v[20:21]
	v_cvt_pk_bf16_f32 v14, v14, v15
	v_pk_mul_f32 v[18:19], v[26:27], v[34:35] op_sel_hi:[1,0]
	v_cvt_pk_bf16_f32 v15, v16, v17
	global_store_dwordx2 v[2:3], v[14:15], off offset:1024
	global_load_dwordx4 v[14:17], v[0:1], off offset:3072
	v_pk_mul_f32 v[20:21], v[28:29], v[34:35] op_sel_hi:[1,0]
	s_waitcnt vmcnt(0)
	v_pk_mul_f32 v[14:15], v[18:19], v[14:15]
	v_pk_mul_f32 v[16:17], v[20:21], v[16:17]
	v_cvt_pk_bf16_f32 v14, v14, v15
	s_nop 0
	v_cvt_pk_bf16_f32 v15, v16, v17
	global_store_dwordx2 v[2:3], v[14:15], off offset:1536
	v_lshl_add_u64 v[2:3], v[2:3], 0, s[4:5]
	s_cbranch_scc0 .LBB0_284

; __device__ __forceinline__ float bflo(unsigned w) { return __uint_as_float(w << 16); }
; __device__ __forceinline__ float bfhi(unsigned w) { return __uint_as_float(w & 0xffff0000u); }
; __device__ __forceinline__ unsigned pkbf(float lo, float hi) { return pg8::cvt_pk_bf16(lo, hi); }
; __device__ __forceinline__ void p5_row(const P& p, int row, int lane) {
;     ...
;     { unsigned* q = (unsigned*)(za + lane * 6); const unsigned w0 = q[0], w1 = q[1], w2 = q[2];
;       float f[6] = {bflo(w0), bfhi(w0), bflo(w1), bfhi(w1), bflo(w2), bfhi(w2)}; float s = 0.f;
; #pragma unroll
;       for (int e = 0; e < 6; ++e) s += f[e] * f[e];
;       const float rstd = 1.0f / sqrtf(wave_sum(s) * (1.f / 384.f) + NORM_EPS); const float* g = p.in[8] + lane * 6;
; #pragma unroll
;       for (int e = 0; e < 6; ++e) f[e] = f[e] * rstd * g[e];
;       q[0] = pkbf(f[0], f[1]); q[1] = pkbf(f[2], f[3]); q[2] = pkbf(f[4], f[5]); }
;     { unsigned* q = (unsigned*)(za + 384 + lane * 4); const unsigned w0 = q[0], w1 = q[1];
;       float f[4] = {bflo(w0), bfhi(w0), bflo(w1), bfhi(w1)}; float s = 0.f;
; #pragma unroll
;       for (int e = 0; e < 4; ++e) s += f[e] * f[e];
;       const float rstd = 1.0f / sqrtf(wave_sum(s) * (1.f / 256.f) + NORM_EPS); const float* g = p.in[10] + lane * 4;
; #pragma unroll
;       for (int e = 0; e < 4; ++e) f[e] = f[e] * rstd * g[e];
;       q[0] = pkbf(f[0], f[1]); q[1] = pkbf(f[2], f[3]); }
;     if (lane < 16) { const float x1 = __uint_as_float((unsigned)za[640 + lane] << 16), x2 = __uint_as_float((unsigned)za[656 + lane] << 16);
;       const float* rp = (const float*)(ws + WS_ROPE) + ((size_t)seq_pos(row) * 16 + lane) * 2; const float c = rp[0], s = rp[1];
;       const unsigned w = pkbf(x1 * c - x2 * s, x1 * s + x2 * c);
;       unsigned* kr = (unsigned*)((bf16_t*)((unsigned char*)p.out + DO_K) + (size_t)row * 768 + 64) + lane;
; #pragma unroll
;       for (int h = 0; h < NH; ++h) kr[h * 48] = w; }
.LBB0_419:
	v_lshl_add_u64 v[0:1], s[50:51], 0, v[26:27]
	v_add_co_u32_e32 v4, vcc, 0x12000000, v0
	s_nop 1
	v_addc_co_u32_e32 v5, vcc, 0, v1, vcc
	global_load_dwordx3 v[0:2], v[4:5], off
	s_waitcnt vmcnt(0)
	v_lshlrev_b32_e32 v6, 16, v0
	v_and_b32_e32 v10, 0xffff0000, v0
	v_lshlrev_b32_e32 v34, 16, v1
	v_and_b32_e32 v35, 0xffff0000, v1
	global_load_dwordx4 v[42:45], v[12:13], off
	global_load_dwordx2 v[0:1], v[12:13], off offset:16
	v_mul_f32_e32 v8, v10, v10
	v_fmac_f32_e32 v8, v6, v6
	v_fmac_f32_e32 v8, v34, v34
	v_lshlrev_b32_e32 v41, 16, v2
	v_fmac_f32_e32 v8, v35, v35
	v_and_b32_e32 v2, 0xffff0000, v2
	v_fmac_f32_e32 v8, v41, v41
	v_fmac_f32_e32 v8, v2, v2
	s_nop 1
	v_add_f32_dpp v8, v8, v8 quad_perm:[1,0,3,2] row_mask:0xf bank_mask:0xf bound_ctrl:1
	s_nop 1
	v_add_f32_dpp v8, v8, v8 quad_perm:[2,3,0,1] row_mask:0xf bank_mask:0xf bound_ctrl:1
	s_nop 1
	v_add_f32_dpp v8, v8, v8 row_half_mirror row_mask:0xf bank_mask:0xf bound_ctrl:1
	s_nop 1
	v_add_f32_dpp v8, v8, v8 row_mirror row_mask:0xf bank_mask:0xf bound_ctrl:1
	s_nop 0
	v_readlane_b32 s98, v8, 0
	v_readlane_b32 s99, v8, 16
	v_readlane_b32 s100, v8, 32
	v_readlane_b32 s101, v8, 48
	v_mov_b32_e32 v8, s98
	v_add_f32_e32 v8, s99, v8
	v_mov_b32_e32 v9, s100
	v_add_f32_e32 v9, s101, v9
	v_add_f32_e32 v8, v8, v9
	v_fmamk_f32 v8, v8, 0x3b2aaaab, v39
	v_mul_f32_e32 v9, 0x4f800000, v8
	v_cmp_gt_f32_e32 vcc, s24, v8
	s_nop 1
	v_cndmask_b32_e32 v46, v8, v9, vcc
	v_sqrt_f32_e32 v47, v46
	v_lshl_add_u64 v[8:9], s[50:51], 0, v[24:25]
	v_add_u32_e32 v48, -1, v47
	v_add_u32_e32 v49, 1, v47
	v_fma_f32 v50, -v48, v47, v46
	v_fma_f32 v51, -v49, v47, v46
	v_cmp_ge_f32_e64 s[0:1], 0, v50
	s_nop 1
	v_cndmask_b32_e64 v47, v47, v48, s[0:1]
	v_cmp_lt_f32_e64 s[0:1], 0, v51
	s_nop 1
	v_cndmask_b32_e64 v47, v47, v49, s[0:1]
	v_mul_f32_e32 v48, 0x37800000, v47
	v_cndmask_b32_e32 v47, v47, v48, vcc
	v_cmp_class_f32_e32 vcc, v46, v40
	s_nop 1
	v_cndmask_b32_e32 v46, v47, v46, vcc
	v_div_scale_f32 v47, s[0:1], v46, v46, 1.0
	v_rcp_f32_e32 v48, v47
	v_add_co_u32_e32 v8, vcc, s3, v8
	v_fma_f32 v50, -v47, v48, 1.0
	s_nop 0
	v_addc_co_u32_e32 v9, vcc, 0, v9, vcc
	v_div_scale_f32 v49, vcc, 1.0, v46, 1.0
	v_fmac_f32_e32 v48, v50, v48
	v_mul_f32_e32 v50, v49, v48
	v_fma_f32 v51, -v47, v50, v49
	v_fmac_f32_e32 v50, v51, v48
	v_fma_f32 v47, -v47, v50, v49
	v_div_fmas_f32 v47, v47, v48, v50
	v_div_fixup_f32 v46, v47, v46, 1.0
	v_mul_f32_e32 v6, v46, v6
	v_mul_f32_e32 v10, v46, v10
	v_mul_f32_e32 v41, v46, v41
	v_mul_f32_e32 v2, v46, v2
	v_mul_f32_e32 v34, v46, v34
	v_mul_f32_e32 v35, v46, v35
	s_waitcnt vmcnt(1)
	v_mul_f32_e32 v6, v42, v6
	v_mul_f32_e32 v10, v43, v10
	s_waitcnt vmcnt(0)
	v_mul_f32_e32 v0, v0, v41
	v_mul_f32_e32 v1, v1, v2
	v_cvt_pk_bf16_f32 v2, v6, v10
	v_mul_f32_e32 v34, v44, v34
	v_mul_f32_e32 v35, v45, v35
	global_store_dword v[4:5], v2, off
	v_cvt_pk_bf16_f32 v2, v34, v35
	global_store_dword v[4:5], v2, off offset:4
	v_cvt_pk_bf16_f32 v0, v0, v1
	global_store_dword v[4:5], v0, off offset:8
	global_load_dwordx2 v[0:1], v[8:9], off offset:768
	s_nop 0
	global_load_dwordx4 v[42:45], v[14:15], off
	s_waitcnt vmcnt(1)
	v_lshlrev_b32_e32 v2, 16, v0
	v_and_b32_e32 v0, 0xffff0000, v0
	v_mul_f32_e32 v5, v0, v0
	v_lshlrev_b32_e32 v4, 16, v1
	v_fmac_f32_e32 v5, v2, v2
	v_and_b32_e32 v1, 0xffff0000, v1
	v_fmac_f32_e32 v5, v4, v4
	v_fmac_f32_e32 v5, v1, v1
	s_nop 1
	v_add_f32_dpp v5, v5, v5 quad_perm:[1,0,3,2] row_mask:0xf bank_mask:0xf bound_ctrl:1
	s_nop 1
	v_add_f32_dpp v5, v5, v5 quad_perm:[2,3,0,1] row_mask:0xf bank_mask:0xf bound_ctrl:1
	s_nop 1
	v_add_f32_dpp v5, v5, v5 row_half_mirror row_mask:0xf bank_mask:0xf bound_ctrl:1
	s_nop 1
	v_add_f32_dpp v5, v5, v5 row_mirror row_mask:0xf bank_mask:0xf bound_ctrl:1
	s_nop 0
	v_readlane_b32 s98, v5, 0
	v_readlane_b32 s99, v5, 16
	v_readlane_b32 s100, v5, 32
	v_readlane_b32 s101, v5, 48
	v_mov_b32_e32 v5, s98
	v_add_f32_e32 v5, s99, v5
	v_mov_b32_e32 v6, s100
	v_add_f32_e32 v6, s101, v6
	v_add_f32_e32 v5, v5, v6
	v_fmamk_f32 v5, v5, 0x3b800000, v39
	v_mul_f32_e32 v6, 0x4f800000, v5
	v_cmp_gt_f32_e32 vcc, s24, v5
	s_nop 1
	v_cndmask_b32_e32 v5, v5, v6, vcc
	v_sqrt_f32_e32 v6, v5
	s_nop 0
	v_add_u32_e32 v10, -1, v6
	v_add_u32_e32 v34, 1, v6
	v_fma_f32 v35, -v10, v6, v5
	v_fma_f32 v41, -v34, v6, v5
	v_cmp_ge_f32_e64 s[0:1], 0, v35
	s_nop 1
	v_cndmask_b32_e64 v6, v6, v10, s[0:1]
	v_cmp_lt_f32_e64 s[0:1], 0, v41
	s_nop 1
	v_cndmask_b32_e64 v6, v6, v34, s[0:1]
	v_mul_f32_e32 v10, 0x37800000, v6
	v_cndmask_b32_e32 v6, v6, v10, vcc
	v_cmp_class_f32_e32 vcc, v5, v40
	s_nop 1
	v_cndmask_b32_e32 v5, v6, v5, vcc
	v_div_scale_f32 v6, s[0:1], v5, v5, 1.0
	v_rcp_f32_e32 v10, v6
	v_div_scale_f32 v34, vcc, 1.0, v5, 1.0
	v_fma_f32 v35, -v6, v10, 1.0
	v_fmac_f32_e32 v10, v35, v10
	v_mul_f32_e32 v35, v34, v10
	v_fma_f32 v41, -v6, v35, v34
	v_fmac_f32_e32 v35, v41, v10
	v_fma_f32 v6, -v6, v35, v34
	v_div_fmas_f32 v6, v6, v10, v35
	v_div_fixup_f32 v5, v6, v5, 1.0
	v_mul_f32_e32 v0, v5, v0
	v_mul_f32_e32 v2, v5, v2
	s_waitcnt vmcnt(0)
	v_mul_f32_e32 v0, v43, v0
	v_mul_f32_e32 v4, v5, v4
	v_mul_f32_e32 v1, v5, v1
	v_mul_f32_e32 v2, v42, v2
	v_cvt_pk_bf16_f32 v0, v2, v0
	v_mul_f32_e32 v4, v44, v4
	v_mul_f32_e32 v1, v45, v1
	global_store_dword v[8:9], v0, off offset:768
	v_cvt_pk_bf16_f32 v0, v4, v1
	global_store_dword v[8:9], v0, off offset:772
	s_and_saveexec_b64 s[0:1], s[4:5]
	s_xor_b64 s[0:1], exec, s[0:1]
	s_and_b32 s14, s26, 0x1fff
	s_add_i32 s15, s26, 0xffff8000
	s_or_saveexec_b64 s[0:1], s[0:1]
	v_mov_b32_e32 v4, s15
	v_mov_b32_e32 v5, s14
	s_xor_b64 exec, exec, s[0:1]
	s_cbranch_execz .LBB0_423
	s_and_b32 s27, s26, 0x1fff
	s_add_i32 s28, s26, 0xffff8000
	v_lshl_add_u64 v[0:1], s[50:51], 0, v[28:29]
	s_cmp_lt_i32 s26, 0x8000
	v_add_co_u32_e32 v0, vcc, 0x12000000, v0
	s_cselect_b32 s18, s27, s28
	s_nop 0
	v_addc_co_u32_e32 v1, vcc, 0, v1, vcc
	s_lshl_b64 s[14:15], s[18:19], 7
	v_lshl_add_u64 v[4:5], v[16:17], 0, s[14:15]
	global_load_ushort v2, v[0:1], off offset:1280
	global_load_ushort v6, v[0:1], off offset:1312
	s_nop 0
	global_load_dwordx2 v[0:1], v[4:5], off
	v_mov_b32_e32 v4, s28
	s_waitcnt vmcnt(2)
	v_lshlrev_b32_e32 v2, 16, v2
	s_waitcnt vmcnt(1)
	v_lshlrev_b32_e32 v5, 16, v6
	s_waitcnt vmcnt(0)
	v_mul_f32_e32 v6, v1, v5
	v_mul_f32_e32 v5, v0, v5
	v_fma_f32 v0, v0, v2, -v6
	v_fmac_f32_e32 v5, v1, v2
	v_cvt_pk_bf16_f32 v0, v0, v5
	v_mov_b32_e32 v5, s27
	global_store_dword v[30:31], v0, off
	global_store_dword v[30:31], v0, off offset:192
	global_store_dword v[30:31], v0, off offset:384
	global_store_dword v[30:31], v0, off offset:576
	global_store_dword v[30:31], v0, off offset:768
	global_store_dword v[30:31], v0, off offset:960
	global_store_dword v[30:31], v0, off offset:1152
	global_store_dword v[30:31], v0, off offset:1344

; __device__ __forceinline__ unsigned pkbf(float lo, float hi) { return pg8::cvt_pk_bf16(lo, hi); }
; __device__ __forceinline__ void unpack8bf(const u32x4 w, float* f) { f[0] = bflo(w.x); f[1] = bfhi(w.x); f[2] = bflo(w.y); f[3] = bfhi(w.y); f[4] = bflo(w.z); f[5] = bfhi(w.z); f[6] = bflo(w.w); f[7] = bfhi(w.w); }
; __device__ __forceinline__ void p10_att_row(const P& p, int row, int lane) {
;     ...
;     { u32x4* q = (u32x4*)(mix + lane * 8); const u32x4 w = *q; float f[8]; unpack8bf(w, f); float s = 0.f;
; #pragma unroll
;       for (int e = 0; e < 8; ++e) s += f[e] * f[e];
;       const float rstd = 1.0f / sqrtf(wave_sum(s) * (1.f / 512.f) + NORM_EPS); const float* g = p.in[12] + lane * 8;
; #pragma unroll
;       for (int e = 0; e < 8; ++e) f[e] = f[e] * rstd * g[e];
;       u32x4 o; o.x = pkbf(f[0], f[1]); o.y = pkbf(f[2], f[3]); o.z = pkbf(f[4], f[5]); o.w = pkbf(f[6], f[7]); *q = o; }
.LBB0_960:
	global_load_dwordx4 v[12:15], v[2:3], off
	global_load_dwordx4 v[16:19], v[0:1], off
	s_addk_i32 s3, 0x100
	s_cmp_lt_i32 s3, 0xbf00
	s_waitcnt vmcnt(1)
	v_lshlrev_b32_e32 v20, 16, v12
	v_and_b32_e32 v21, 0xffff0000, v12
	v_lshlrev_b32_e32 v22, 16, v13
	v_and_b32_e32 v23, 0xffff0000, v13
	v_lshlrev_b32_e32 v24, 16, v14
	v_and_b32_e32 v25, 0xffff0000, v14
	v_lshlrev_b32_e32 v26, 16, v15
	v_and_b32_e32 v27, 0xffff0000, v15
	global_load_dwordx4 v[12:15], v[0:1], off offset:16
	v_mul_f32_e32 v28, v21, v21
	v_fmac_f32_e32 v28, v20, v20
	v_fmac_f32_e32 v28, v22, v22
	v_fmac_f32_e32 v28, v23, v23
	v_fmac_f32_e32 v28, v24, v24
	v_fmac_f32_e32 v28, v25, v25
	v_fmac_f32_e32 v28, v26, v26
	v_fmac_f32_e32 v28, v27, v27
	s_nop 1
	v_add_f32_dpp v28, v28, v28 quad_perm:[1,0,3,2] row_mask:0xf bank_mask:0xf bound_ctrl:1
	s_nop 1
	v_add_f32_dpp v28, v28, v28 quad_perm:[2,3,0,1] row_mask:0xf bank_mask:0xf bound_ctrl:1
	s_nop 1
	v_add_f32_dpp v28, v28, v28 row_half_mirror row_mask:0xf bank_mask:0xf bound_ctrl:1
	s_nop 1
	v_add_f32_dpp v28, v28, v28 row_mirror row_mask:0xf bank_mask:0xf bound_ctrl:1
	s_nop 0
	v_readlane_b32 s98, v28, 0
	v_readlane_b32 s99, v28, 16
	v_readlane_b32 s100, v28, 32
	v_readlane_b32 s101, v28, 48
	v_mov_b32_e32 v28, s98
	v_add_f32_e32 v28, s99, v28
	v_mov_b32_e32 v29, s100
	v_add_f32_e32 v29, s101, v29
	v_add_f32_e32 v28, v28, v29
	v_fmamk_f32 v28, v28, 0x3b000000, v10
	v_mul_f32_e32 v29, 0x4f800000, v28
	v_cmp_gt_f32_e32 vcc, s6, v28
	s_nop 1
	v_cndmask_b32_e32 v28, v28, v29, vcc
	v_sqrt_f32_e32 v29, v28
	s_nop 0
	v_add_u32_e32 v30, -1, v29
	v_add_u32_e32 v31, 1, v29
	v_fma_f32 v32, -v30, v29, v28
	v_fma_f32 v33, -v31, v29, v28
	v_cmp_ge_f32_e64 s[0:1], 0, v32
	s_nop 1
	v_cndmask_b32_e64 v29, v29, v30, s[0:1]
	v_cmp_lt_f32_e64 s[0:1], 0, v33
	s_nop 1
	v_cndmask_b32_e64 v29, v29, v31, s[0:1]
	v_mul_f32_e32 v30, 0x37800000, v29
	v_cndmask_b32_e32 v29, v29, v30, vcc
	v_cmp_class_f32_e32 vcc, v28, v11
	s_nop 1
	v_cndmask_b32_e32 v28, v29, v28, vcc
	v_div_scale_f32 v29, s[0:1], v28, v28, 1.0
	v_rcp_f32_e32 v30, v29
	v_div_scale_f32 v31, vcc, 1.0, v28, 1.0
	v_fma_f32 v32, -v29, v30, 1.0
	v_fmac_f32_e32 v30, v32, v30
	v_mul_f32_e32 v32, v31, v30
	v_fma_f32 v33, -v29, v32, v31
	v_fmac_f32_e32 v32, v33, v30
	v_fma_f32 v29, -v29, v32, v31
	v_div_fmas_f32 v29, v29, v30, v32
	v_div_fixup_f32 v28, v29, v28, 1.0
	v_mul_f32_e32 v27, v28, v27
	v_mul_f32_e32 v20, v28, v20
	v_mul_f32_e32 v21, v28, v21
	v_mul_f32_e32 v22, v28, v22
	v_mul_f32_e32 v23, v28, v23
	v_mul_f32_e32 v24, v28, v24
	v_mul_f32_e32 v25, v28, v25
	v_mul_f32_e32 v26, v28, v26
	s_waitcnt vmcnt(0)
	v_mul_f32_e32 v15, v15, v27
	v_mul_f32_e32 v16, v16, v20
	v_mul_f32_e32 v17, v17, v21
	v_mul_f32_e32 v18, v18, v22
	v_mul_f32_e32 v19, v19, v23
	v_mul_f32_e32 v20, v12, v24
	v_mul_f32_e32 v21, v13, v25
	v_mul_f32_e32 v22, v14, v26
	v_cvt_pk_bf16_f32 v12, v16, v17
	v_cvt_pk_bf16_f32 v13, v18, v19
	v_cvt_pk_bf16_f32 v14, v20, v21
	v_cvt_pk_bf16_f32 v15, v22, v15
	global_store_dwordx4 v[2:3], v[12:15], off
	v_lshl_add_u64 v[2:3], v[2:3], 0, s[4:5]
	s_cbranch_scc1 .LBB0_960

; __device__ __forceinline__ unsigned pkbf(float lo, float hi) { return pg8::cvt_pk_bf16(lo, hi); }
; __device__ __forceinline__ void unpack8bf(const u32x4 w, float* f) { f[0] = bflo(w.x); f[1] = bfhi(w.x); f[2] = bflo(w.y); f[3] = bfhi(w.y); f[4] = bflo(w.z); f[5] = bfhi(w.z); f[6] = bflo(w.w); f[7] = bfhi(w.w); }
; __device__ __forceinline__ void norm_row_bf(const bf16_t* src, const float* gain, bf16_t* ob, float* of, int lane) {
;     float v[16]; float s = 0.f;
;     const u32x4 w0 = *((const u32x4*)src + lane), w1 = *((const u32x4*)src + lane + 64);
;     unpack8bf(w0, v); unpack8bf(w1, v + 8);
; #pragma unroll
;     for (int e = 0; e < 16; ++e) s += v[e] * v[e];
;     const float rstd = 1.0f / sqrtf(wave_sum(s) * (1.f / DM) + NORM_EPS);
; #pragma unroll
;     for (int h = 0; h < 2; ++h) { const float* g = gain + h * 512 + lane * 8; const f32x4 g0 = *(const f32x4*)g, g1 = *(const f32x4*)(g + 4);
;         float o[8];
; #pragma unroll
;         for (int e = 0; e < 4; ++e) { o[e] = v[h * 8 + e] * rstd * g0[e]; o[4 + e] = v[h * 8 + 4 + e] * rstd * g1[e]; }
;         if (ob) { u32x4 w; w.x = pkbf(o[0], o[1]); w.y = pkbf(o[2], o[3]); w.z = pkbf(o[4], o[5]); w.w = pkbf(o[6], o[7]); *((u32x4*)ob + lane + 64 * h) = w; }
;         else { const f32x4 a = {o[0], o[1], o[2], o[3]}, b = {o[4], o[5], o[6], o[7]}; *(f32x4*)(of + h * 512 + lane * 8) = a; *(f32x4*)(of + h * 512 + lane * 8 + 4) = b; } }
; }
.LBB0_1302:
	v_add_co_u32_e32 v12, vcc, 0xe9800000, v2
	s_add_i32 s6, s6, s88
	s_nop 0
	v_addc_co_u32_e32 v13, vcc, -1, v3, vcc
	global_load_dwordx4 v[12:15], v[12:13], off nt
	v_add_co_u32_e32 v28, vcc, 0xe9801000, v2
	s_cmp_gt_i32 s6, 0xbfff
	s_nop 0
	v_addc_co_u32_e32 v29, vcc, -1, v3, vcc
	global_load_dwordx4 v[16:19], v[28:29], off offset:-3072 nt
	global_load_dwordx4 v[20:23], v[0:1], off offset:16
	global_load_dwordx4 v[24:27], v[0:1], off
	s_waitcnt vmcnt(3)
	v_lshlrev_b32_e32 v28, 16, v12
	v_and_b32_e32 v12, 0xffff0000, v12
	v_lshlrev_b32_e32 v29, 16, v13
	v_and_b32_e32 v13, 0xffff0000, v13
	s_waitcnt vmcnt(2)
	v_lshlrev_b32_e32 v32, 16, v16
	v_and_b32_e32 v33, 0xffff0000, v16
	v_mul_f32_e32 v16, v12, v12
	v_fmac_f32_e32 v16, v28, v28
	v_fmac_f32_e32 v16, v29, v29
	v_lshlrev_b32_e32 v30, 16, v14
	v_fmac_f32_e32 v16, v13, v13
	v_and_b32_e32 v14, 0xffff0000, v14
	v_fmac_f32_e32 v16, v30, v30
	v_lshlrev_b32_e32 v31, 16, v15
	v_fmac_f32_e32 v16, v14, v14
	v_and_b32_e32 v15, 0xffff0000, v15
	v_fmac_f32_e32 v16, v31, v31
	v_fmac_f32_e32 v16, v15, v15
	v_fmac_f32_e32 v16, v32, v32
	v_lshlrev_b32_e32 v34, 16, v17
	v_fmac_f32_e32 v16, v33, v33
	v_and_b32_e32 v35, 0xffff0000, v17
	v_fmac_f32_e32 v16, v34, v34
	v_lshlrev_b32_e32 v36, 16, v18
	v_fmac_f32_e32 v16, v35, v35
	v_and_b32_e32 v37, 0xffff0000, v18
	v_fmac_f32_e32 v16, v36, v36
	v_lshlrev_b32_e32 v38, 16, v19
	v_fmac_f32_e32 v16, v37, v37
	v_and_b32_e32 v39, 0xffff0000, v19
	v_fmac_f32_e32 v16, v38, v38
	v_fmac_f32_e32 v16, v39, v39
	s_nop 1
	v_add_f32_dpp v16, v16, v16 quad_perm:[1,0,3,2] row_mask:0xf bank_mask:0xf bound_ctrl:1
	s_nop 1
	v_add_f32_dpp v16, v16, v16 quad_perm:[2,3,0,1] row_mask:0xf bank_mask:0xf bound_ctrl:1
	s_nop 1
	v_add_f32_dpp v16, v16, v16 row_half_mirror row_mask:0xf bank_mask:0xf bound_ctrl:1
	s_nop 1
	v_add_f32_dpp v16, v16, v16 row_mirror row_mask:0xf bank_mask:0xf bound_ctrl:1
	s_nop 0
	v_readlane_b32 s98, v16, 0
	v_readlane_b32 s99, v16, 16
	v_readlane_b32 s100, v16, 32
	v_readlane_b32 s101, v16, 48
	v_mov_b32_e32 v16, s98
	v_add_f32_e32 v16, s99, v16
	v_mov_b32_e32 v17, s100
	v_add_f32_e32 v17, s101, v17
	v_add_f32_e32 v16, v16, v17
	v_fmamk_f32 v16, v16, 0x3a800000, v10
	v_mul_f32_e32 v17, 0x4f800000, v16
	v_cmp_gt_f32_e32 vcc, s3, v16
	s_nop 1
	v_cndmask_b32_e32 v16, v16, v17, vcc
	v_sqrt_f32_e32 v17, v16
	s_nop 0
	v_add_u32_e32 v18, -1, v17
	v_add_u32_e32 v19, 1, v17
	v_fma_f32 v40, -v18, v17, v16
	v_fma_f32 v41, -v19, v17, v16
	v_cmp_ge_f32_e64 s[0:1], 0, v40
	s_nop 1
	v_cndmask_b32_e64 v17, v17, v18, s[0:1]
	v_cmp_lt_f32_e64 s[0:1], 0, v41
	s_nop 1
	v_cndmask_b32_e64 v17, v17, v19, s[0:1]
	v_mul_f32_e32 v18, 0x37800000, v17
	v_cndmask_b32_e32 v17, v17, v18, vcc
	v_cmp_class_f32_e32 vcc, v16, v11
	s_nop 1
	v_cndmask_b32_e32 v16, v17, v16, vcc
	v_div_scale_f32 v17, s[0:1], v16, v16, 1.0
	v_rcp_f32_e32 v18, v17
	v_div_scale_f32 v19, vcc, 1.0, v16, 1.0
	v_fma_f32 v40, -v17, v18, 1.0
	v_fmac_f32_e32 v18, v40, v18
	v_mul_f32_e32 v40, v19, v18
	v_fma_f32 v41, -v17, v40, v19
	v_fmac_f32_e32 v40, v41, v18
	v_fma_f32 v17, -v17, v40, v19
	v_div_fmas_f32 v17, v17, v18, v40
	v_div_fixup_f32 v40, v17, v16, 1.0
	v_mul_f32_e32 v12, v40, v12
	v_mul_f32_e32 v14, v40, v14
	v_mul_f32_e32 v13, v40, v13
	v_mul_f32_e32 v15, v40, v15
	v_mul_f32_e32 v16, v40, v28
	v_mul_f32_e32 v17, v40, v30
	v_mul_f32_e32 v18, v40, v29
	v_mul_f32_e32 v19, v40, v31
	s_waitcnt vmcnt(0)
	v_mul_f32_e32 v12, v25, v12
	v_mul_f32_e32 v14, v21, v14
	v_mul_f32_e32 v13, v27, v13
	v_mul_f32_e32 v15, v23, v15
	v_mul_f32_e32 v16, v24, v16
	v_mul_f32_e32 v17, v20, v17
	v_mul_f32_e32 v18, v26, v18
	v_mul_f32_e32 v19, v22, v19
	v_cvt_pk_bf16_f32 v12, v16, v12
	v_cvt_pk_bf16_f32 v13, v18, v13
	v_cvt_pk_bf16_f32 v14, v17, v14
	v_cvt_pk_bf16_f32 v15, v19, v15
	global_store_dwordx4 v[2:3], v[12:15], off
	global_load_dwordx4 v[12:15], v[0:1], off offset:2048
	s_nop 0
	global_load_dwordx4 v[16:19], v[0:1], off offset:2064
	v_mul_f32_e32 v20, v40, v32
	v_mul_f32_e32 v22, v40, v33
	v_mul_f32_e32 v24, v40, v34
	v_mul_f32_e32 v26, v40, v35
	v_mul_f32_e32 v21, v40, v36
	v_mul_f32_e32 v23, v40, v37
	v_mul_f32_e32 v25, v40, v38
	v_mul_f32_e32 v27, v40, v39
	s_waitcnt vmcnt(1)
	v_mul_f32_e32 v12, v12, v20
	v_mul_f32_e32 v13, v13, v22
	v_mul_f32_e32 v14, v14, v24
	v_mul_f32_e32 v15, v15, v26
	s_waitcnt vmcnt(0)
	v_mul_f32_e32 v16, v16, v21
	v_mul_f32_e32 v17, v17, v23
	v_mul_f32_e32 v18, v18, v25
	v_mul_f32_e32 v19, v19, v27
	v_cvt_pk_bf16_f32 v12, v12, v13
	v_cvt_pk_bf16_f32 v13, v14, v15
	v_cvt_pk_bf16_f32 v14, v16, v17
	v_cvt_pk_bf16_f32 v15, v18, v19
	global_store_dwordx4 v[2:3], v[12:15], off offset:1024
	v_lshl_add_u64 v[2:3], v[2:3], 0, s[4:5]
	s_cbranch_scc0 .LBB0_1302

; __device__ __forceinline__ unsigned pkbf(float lo, float hi) { return pg8::cvt_pk_bf16(lo, hi); }
; __device__ __forceinline__ void unpack8bf(const u32x4 w, float* f) { f[0] = bflo(w.x); f[1] = bfhi(w.x); f[2] = bflo(w.y); f[3] = bfhi(w.y); f[4] = bflo(w.z); f[5] = bfhi(w.z); f[6] = bflo(w.w); f[7] = bfhi(w.w); }
; __device__ __forceinline__ float wave_sum(float v) {
; #pragma unroll
;     for (int o = 1; o < 64; o <<= 1) v += __shfl_xor(v, o);
;     return v;
; }
; __device__ __forceinline__ void norm_row_bf(const bf16_t* src, const float* gain, bf16_t* ob, float* of, int lane) {
;     float v[16]; float s = 0.f;
;     const u32x4 w0 = *((const u32x4*)src + lane), w1 = *((const u32x4*)src + lane + 64);
;     unpack8bf(w0, v); unpack8bf(w1, v + 8);
; #pragma unroll
;     for (int e = 0; e < 16; ++e) s += v[e] * v[e];
;     const float rstd = 1.0f / sqrtf(wave_sum(s) * (1.f / DM) + NORM_EPS);
; #pragma unroll
;     for (int h = 0; h < 2; ++h) { const float* g = gain + h * 512 + lane * 8; const f32x4 g0 = *(const f32x4*)g, g1 = *(const f32x4*)(g + 4);
;         float o[8];
; #pragma unroll
;         for (int e = 0; e < 4; ++e) { o[e] = v[h * 8 + e] * rstd * g0[e]; o[4 + e] = v[h * 8 + 4 + e] * rstd * g1[e]; }
;         if (ob) { u32x4 w; w.x = pkbf(o[0], o[1]); w.y = pkbf(o[2], o[3]); w.z = pkbf(o[4], o[5]); w.w = pkbf(o[6], o[7]); *((u32x4*)ob + lane + 64 * h) = w; }
;         else { const f32x4 a = {o[0], o[1], o[2], o[3]}, b = {o[4], o[5], o[6], o[7]}; *(f32x4*)(of + h * 512 + lane * 8) = a; *(f32x4*)(of + h * 512 + lane * 8 + 4) = b; } }
; }
.LBB0_1501:
	global_load_dwordx4 v[14:17], v[2:3], off
	global_load_dwordx4 v[18:21], v[2:3], off offset:1024
	global_load_dwordx4 v[22:25], v[0:1], off offset:16
	global_load_dwordx4 v[26:29], v[0:1], off
	s_add_i32 s34, s34, s88
	v_lshl_add_u64 v[2:3], v[2:3], 0, s[2:3]
	s_cmp_gt_i32 s34, 0xbfff
	s_waitcnt vmcnt(3)
	v_lshlrev_b32_e32 v34, 16, v14
	v_and_b32_e32 v35, 0xffff0000, v14
	v_lshlrev_b32_e32 v14, 16, v15
	v_and_b32_e32 v15, 0xffff0000, v15
	v_pk_mul_f32 v[44:45], v[34:35], v[34:35]
	v_pk_mul_f32 v[46:47], v[14:15], v[14:15]
	v_add_f32_e32 v44, v44, v45
	v_lshlrev_b32_e32 v32, 16, v16
	v_and_b32_e32 v33, 0xffff0000, v16
	v_add_f32_e32 v44, v46, v44
	s_waitcnt vmcnt(2)
	v_and_b32_e32 v30, 0xffff0000, v21
	v_lshlrev_b32_e32 v31, 16, v21
	v_lshlrev_b32_e32 v36, 16, v20
	v_and_b32_e32 v37, 0xffff0000, v20
	v_pk_mul_f32 v[20:21], v[32:33], v[32:33]
	v_add_f32_e32 v44, v47, v44
	v_lshlrev_b32_e32 v16, 16, v17
	v_and_b32_e32 v17, 0xffff0000, v17
	v_add_f32_e32 v20, v20, v44
	v_pk_mul_f32 v[42:43], v[16:17], v[16:17]
	v_add_f32_e32 v20, v21, v20
	v_lshlrev_b32_e32 v38, 16, v18
	v_and_b32_e32 v39, 0xffff0000, v18
	v_add_f32_e32 v20, v42, v20
	v_pk_mul_f32 v[50:51], v[38:39], v[38:39]
	v_add_f32_e32 v20, v43, v20
	v_lshlrev_b32_e32 v40, 16, v19
	v_and_b32_e32 v41, 0xffff0000, v19
	v_add_f32_e32 v20, v50, v20
	v_pk_mul_f32 v[52:53], v[40:41], v[40:41]
	v_add_f32_e32 v20, v51, v20
	v_add_f32_e32 v20, v52, v20
	v_pk_mul_f32 v[48:49], v[36:37], v[36:37]
	v_add_f32_e32 v20, v53, v20
	v_add_f32_e32 v20, v48, v20
	v_pk_mul_f32 v[18:19], v[30:31], v[30:31]
	v_add_f32_e32 v20, v49, v20
	v_add_f32_e32 v19, v19, v20
	v_add_f32_e32 v18, v18, v19
	s_nop 1
	v_add_f32_dpp v18, v18, v18 quad_perm:[1,0,3,2] row_mask:0xf bank_mask:0xf bound_ctrl:1
	s_nop 1
	v_add_f32_dpp v18, v18, v18 quad_perm:[2,3,0,1] row_mask:0xf bank_mask:0xf bound_ctrl:1
	s_nop 1
	v_add_f32_dpp v18, v18, v18 row_half_mirror row_mask:0xf bank_mask:0xf bound_ctrl:1
	s_nop 1
	v_add_f32_dpp v18, v18, v18 row_mirror row_mask:0xf bank_mask:0xf bound_ctrl:1
	s_nop 0
	v_readlane_b32 s98, v18, 0
	v_readlane_b32 s99, v18, 16
	v_readlane_b32 s100, v18, 32
	v_readlane_b32 s101, v18, 48
	v_mov_b32_e32 v18, s98
	v_add_f32_e32 v18, s99, v18
	v_mov_b32_e32 v19, s100
	v_add_f32_e32 v19, s101, v19
	v_add_f32_e32 v18, v18, v19
	v_fmamk_f32 v18, v18, 0x3a800000, v12
	v_mul_f32_e32 v19, 0x4f800000, v18
	v_cmp_gt_f32_e32 vcc, s6, v18
	s_nop 1
	v_cndmask_b32_e32 v18, v18, v19, vcc
	v_sqrt_f32_e32 v19, v18
	s_nop 0
	v_add_u32_e32 v20, -1, v19
	v_add_u32_e32 v21, 1, v19
	v_fma_f32 v42, -v20, v19, v18
	v_fma_f32 v43, -v21, v19, v18
	v_cmp_ge_f32_e64 s[0:1], 0, v42
	s_nop 1
	v_cndmask_b32_e64 v19, v19, v20, s[0:1]
	v_cmp_lt_f32_e64 s[0:1], 0, v43
	s_nop 1
	v_cndmask_b32_e64 v19, v19, v21, s[0:1]
	v_mul_f32_e32 v20, 0x37800000, v19
	v_cndmask_b32_e32 v19, v19, v20, vcc
	v_cmp_class_f32_e32 vcc, v18, v13
	s_nop 1
	v_cndmask_b32_e32 v18, v19, v18, vcc
	v_div_scale_f32 v19, s[0:1], v18, v18, 1.0
	v_rcp_f32_e32 v21, v19
	v_div_scale_f32 v20, vcc, 1.0, v18, 1.0
	v_fma_f32 v42, -v19, v21, 1.0
	v_fmac_f32_e32 v21, v42, v21
	v_mul_f32_e32 v42, v20, v21
	v_fma_f32 v43, -v19, v42, v20
	v_fmac_f32_e32 v42, v43, v21
	v_fma_f32 v19, -v19, v42, v20
	v_div_fmas_f32 v19, v19, v21, v42
	v_div_fixup_f32 v42, v19, v18, 1.0
	v_pk_mul_f32 v[18:19], v[42:43], v[34:35] op_sel_hi:[0,1]
	v_pk_mul_f32 v[14:15], v[42:43], v[14:15] op_sel_hi:[0,1]
	v_pk_mul_f32 v[32:33], v[42:43], v[32:33] op_sel_hi:[0,1]
	v_pk_mul_f32 v[20:21], v[42:43], v[16:17] op_sel_hi:[0,1]
	s_waitcnt vmcnt(0)
	v_pk_mul_f32 v[16:17], v[28:29], v[14:15]
	v_pk_mul_f32 v[14:15], v[26:27], v[18:19]
	v_pk_mul_f32 v[20:21], v[24:25], v[20:21]
	v_pk_mul_f32 v[18:19], v[22:23], v[32:33]
	global_store_dwordx4 v[4:5], v[14:17], off nt
	global_store_dwordx4 v[4:5], v[18:21], off offset:16 nt
	global_load_dwordx4 v[14:17], v[0:1], off offset:2048
	s_nop 0
	global_load_dwordx4 v[18:21], v[0:1], off offset:2064
	v_pk_mul_f32 v[26:27], v[42:43], v[40:41] op_sel_hi:[0,1]
	v_pk_mul_f32 v[28:29], v[42:43], v[38:39] op_sel_hi:[0,1]
	v_pk_mul_f32 v[22:23], v[42:43], v[36:37] op_sel_hi:[0,1]
	v_pk_mul_f32 v[24:25], v[42:43], v[30:31] op_sel_hi:[0,1]
	s_waitcnt vmcnt(1)
	v_pk_mul_f32 v[14:15], v[14:15], v[28:29]
	v_pk_mul_f32 v[16:17], v[16:17], v[26:27]
	s_waitcnt vmcnt(0)
	v_pk_mul_f32 v[18:19], v[18:19], v[22:23]
	v_pk_mul_f32 v[20:21], v[20:21], v[24:25] op_sel:[0,1] op_sel_hi:[1,0]
	global_store_dwordx4 v[4:5], v[14:17], off offset:2048 nt
	global_store_dwordx4 v[4:5], v[18:21], off offset:2064 nt
	v_lshl_add_u64 v[4:5], v[4:5], 0, s[4:5]
	s_cbranch_scc0 .LBB0_1501

; __global__ void __launch_bounds__(512, 2) mega_fwd(const Args a) {
;     extern __shared__ __attribute__((aligned(16))) unsigned char lds_raw[];
	.amdhsa_kernel _Z8mega_fwd4Args
		.amdhsa_group_segment_fixed_size 0
		.amdhsa_private_segment_fixed_size 0
		.amdhsa_kernarg_size 512
		.amdhsa_user_sgpr_count 2
		.amdhsa_user_sgpr_dispatch_ptr 0
		.amdhsa_user_sgpr_queue_ptr 0
		.amdhsa_user_sgpr_kernarg_segment_ptr 1
		.amdhsa_user_sgpr_dispatch_id 0
		.amdhsa_user_sgpr_kernarg_preload_length 0
		.amdhsa_user_sgpr_kernarg_preload_offset 0
		.amdhsa_user_sgpr_private_segment_size 0
		.amdhsa_uses_dynamic_stack 0
		.amdhsa_enable_private_segment 0
		.amdhsa_system_sgpr_workgroup_id_x 1
		.amdhsa_system_sgpr_workgroup_id_y 0
		.amdhsa_system_sgpr_workgroup_id_z 0
		.amdhsa_system_sgpr_workgroup_info 0
		.amdhsa_system_vgpr_workitem_id 2
		.amdhsa_next_free_vgpr 238
		.amdhsa_next_free_sgpr 102
		.amdhsa_accum_offset 240
		.amdhsa_reserve_vcc 1
		.amdhsa_float_round_mode_32 0
		.amdhsa_float_round_mode_16_64 0
		.amdhsa_float_denorm_mode_32 3
		.amdhsa_float_denorm_mode_16_64 3
		.amdhsa_dx10_clamp 1
		.amdhsa_ieee_mode 1
		.amdhsa_fp16_overflow 0
		.amdhsa_tg_split 0
		.amdhsa_exception_fp_ieee_invalid_op 0
		.amdhsa_exception_fp_denorm_src 0
		.amdhsa_exception_fp_ieee_div_zero 0
		.amdhsa_exception_fp_ieee_overflow 0
		.amdhsa_exception_fp_ieee_underflow 0
		.amdhsa_exception_fp_ieee_inexact 0
		.amdhsa_exception_int_div_zero 0
	.end_amdhsa_kernel

; __global__ void __launch_bounds__(512, 2) mega_fwd(const Args a) {
amdhsa.kernels:
  - .agpr_count:     0
    .args:
      - .offset:         0
        .size:           256
        .value_kind:     by_value
      - .offset:         256
        .size:           4
        .value_kind:     hidden_block_count_x
      - .offset:         260
        .size:           4
        .value_kind:     hidden_block_count_y
      - .offset:         264
        .size:           4
        .value_kind:     hidden_block_count_z
      - .offset:         268
        .size:           2
        .value_kind:     hidden_group_size_x
      - .offset:         270
        .size:           2
        .value_kind:     hidden_group_size_y
      - .offset:         272
        .size:           2
        .value_kind:     hidden_group_size_z
      - .offset:         274
        .size:           2
        .value_kind:     hidden_remainder_x
      - .offset:         276
        .size:           2
        .value_kind:     hidden_remainder_y
      - .offset:         278
        .size:           2
        .value_kind:     hidden_remainder_z
      - .offset:         296
        .size:           8
        .value_kind:     hidden_global_offset_x
      - .offset:         304
        .size:           8
        .value_kind:     hidden_global_offset_y
      - .offset:         312
        .size:           8
        .value_kind:     hidden_global_offset_z
      - .offset:         320
        .size:           2
        .value_kind:     hidden_grid_dims
      - .offset:         344
        .size:           8
        .value_kind:     hidden_multigrid_sync_arg
      - .offset:         376
        .size:           4
        .value_kind:     hidden_dynamic_lds_size
    .group_segment_fixed_size: 0
    .kernarg_segment_align: 8
    .kernarg_segment_size: 512
    .language:       OpenCL C
    .language_version:
      - 2
      - 0
    .max_flat_workgroup_size: 512
    .name:           _Z8mega_fwd4Args
    .private_segment_fixed_size: 0
    .sgpr_count:     108
    .sgpr_spill_count: 87
    .symbol:         _Z8mega_fwd4Args.kd
    .uniform_work_group_size: 1
    .uses_dynamic_stack: false
    .vgpr_count:     238
    .vgpr_spill_count: 0
    .wavefront_size: 64
